# P1 epilogue: 64 dead (cos, sin) default moves removed
# speedup vs baseline: 1.0017x; 1.0017x over previous
;     __device__ __forceinline__ void operator()(const f32x4 (&acc)[2][2][4][2], const Unit& u, int wr, int wc, int fr_, int fq_) const {
;     ...
;         const int row0 = u.pm * BM + wr * 64 + fr, colt = u.pn * BM, region = colt >> 10, cl = wc * 32 + 8 * fq;
;         const int crt = (colt & 1023) + cl;
;         const bool rotl = (region <= 1) && ((cl & 63) < 16);
;         const int jb = (cl & 15) >> 1;
;         const f32x2* __restrict__ rp0 = rot + (size_t)(row0 & 4095) * 8 + jb;
;         f32x2 csr[8][4];
; #pragma unroll
;         for (int g = 0; g < 8; ++g)
; #pragma unroll
;             for (int i = 0; i < 4; ++i) csr[g][i] = (f32x2){1.f, 0.f};
;         if (rotl) {
; #pragma unroll
;             for (int g = 0; g < 8; ++g) { const f32x2* __restrict__ rp = rp0 + (size_t)((g >> 2) * HALF + (g & 3) * 16) * 8;
; #pragma unroll
;                 for (int i = 0; i < 4; ++i) csr[g][i] = rp[i]; } }
.LBB0_179:
	v_mov_b32_e32 v226, v1
	v_mov_b32_e32 v58, v195
	s_lshl_b32 s2, s38, 8
	v_lshlrev_b32_e32 v213, 3, v58
	s_add_i32 s2, s2, s77
	v_add_u32_e32 v228, s78, v213
	s_ashr_i32 s27, s0, 2
	v_and_b32_e32 v58, 48, v228
	s_cmp_lt_i32 s27, 2
	v_add_u32_e32 v212, s2, v226
	v_cmp_eq_u32_e32 vcc, 0, v58
	s_cselect_b64 s[38:39], -1, 0
	v_lshlrev_b32_e32 v227, 3, v212
	s_and_b64 s[38:39], s[38:39], vcc
	s_and_saveexec_b64 s[40:41], s[38:39]
	s_cbranch_execz .LBB0_181
	v_and_b32_e32 v58, 0x7ff8, v227
	v_lshlrev_b32_e32 v204, 3, v58
	v_lshlrev_b32_e32 v60, 2, v213
	v_lshl_add_u64 v[58:59], s[6:7], 0, v[204:205]
	v_and_b32_e32 v204, 32, v60
	v_lshl_add_u64 v[58:59], v[58:59], 0, v[204:205]
	s_movk_i32 s2, 0x2000
	s_mov_b64 s[42:43], 0x2000
	v_add_co_u32_e32 v62, vcc, s2, v58
	global_load_dwordx4 v[186:189], v[58:59], off offset:16
	global_load_dwordx4 v[190:193], v[58:59], off
	global_load_dwordx4 v[178:181], v[58:59], off offset:1040
	global_load_dwordx4 v[182:185], v[58:59], off offset:1024
	global_load_dwordx4 v[170:173], v[58:59], off offset:2064
	global_load_dwordx4 v[174:177], v[58:59], off offset:2048
	global_load_dwordx4 v[146:149], v[58:59], off offset:3088
	global_load_dwordx4 v[150:153], v[58:59], off offset:3072
	v_lshl_add_u64 v[60:61], v[58:59], 0, s[42:43]
	v_addc_co_u32_e32 v63, vcc, 0, v59, vcc
	s_mov_b64 s[42:43], 0x2400
	global_load_dwordx4 v[126:129], v[62:63], off
	global_load_dwordx4 v[122:125], v[60:61], off offset:16
	v_lshl_add_u64 v[60:61], v[58:59], 0, s[42:43]
	s_mov_b64 s[42:43], 0x2800
	v_lshl_add_u64 v[78:79], v[58:59], 0, s[42:43]
	s_mov_b64 s[42:43], 0x2c00
	v_lshl_add_u64 v[58:59], v[58:59], 0, s[42:43]
	global_load_dwordx4 v[106:109], v[62:63], off offset:1024
	global_load_dwordx4 v[82:85], v[62:63], off offset:2048
	global_load_dwordx4 v[102:105], v[60:61], off offset:16
	s_nop 0
	global_load_dwordx4 v[62:65], v[62:63], off offset:3072
	s_nop 0
	global_load_dwordx4 v[78:81], v[78:79], off offset:16
	s_nop 0
	global_load_dwordx4 v[58:61], v[58:59], off offset:16
